# final LayerNorm output stores carry nt; on top of nt weight-conversion stores + peeled C=0 first K-iteration + no canonicalizing v_max + MFMA-head trim + barrier XGEN-first
# speedup vs baseline: 1.0092x; 1.0008x over previous
.LBB0_2388:
	s_or_b64 exec, exec, s[2:3]
	v_mov_b32_e32 v96, v124
	v_mov_b32_e32 v97, v136
	v_mov_b32_e32 v98, v125
	v_mov_b32_e32 v99, v137
	v_pk_add_f32 v[96:97], v[96:97], v[98:99]
	v_mov_b32_e32 v98, v126
	v_mov_b32_e32 v99, v120
	v_mov_b32_e32 v100, v127
	v_mov_b32_e32 v101, v121
	v_pk_add_f32 v[98:99], v[98:99], v[100:101]
	v_mov_b32_e32 v100, v139
	v_pk_add_f32 v[96:97], v[98:99], v[96:97]
	v_mov_b32_e32 v98, v138
	v_mov_b32_e32 v99, v122
	v_mov_b32_e32 v101, v123
	v_pk_add_f32 v[98:99], v[98:99], v[100:101]
	v_mov_b32_e32 v100, v114
	v_mov_b32_e32 v101, v142
	v_mov_b32_e32 v102, v115
	v_mov_b32_e32 v103, v143
	v_pk_add_f32 v[100:101], v[100:101], v[102:103]
	v_pk_add_f32 v[96:97], v[96:97], v[96:97] op_sel_hi:[0,1]
	v_pk_add_f32 v[98:99], v[98:99], v[98:99] op_sel_hi:[0,1]
	v_pk_add_f32 v[100:101], v[100:101], v[100:101] op_sel_hi:[0,1]
	v_pk_add_f32 v[102:103], v[112:113], v[112:113] op_sel_hi:[0,1]
	v_pk_add_f32 v[104:105], v[116:117], v[116:117] op_sel_hi:[0,1]
	v_pk_add_f32 v[106:107], v[118:119], v[118:119] op_sel_hi:[0,1]
	v_pk_add_f32 v[108:109], v[140:141], v[140:141] op_sel_hi:[0,1]
	v_mov_b32_e32 v96, v144
	v_mov_b32_e32 v128, v145
	v_mov_b32_e32 v100, v146
	v_mov_b32_e32 v98, v147
	v_pk_add_f32 v[96:97], v[96:97], v[128:129]
	v_pk_add_f32 v[98:99], v[100:101], v[98:99]
	v_mov_b32_e32 v104, v148
	v_mov_b32_e32 v102, v149
	v_mov_b32_e32 v108, v150
	v_mov_b32_e32 v106, v151
	v_pk_add_f32 v[96:97], v[98:99], v[96:97]
	v_pk_add_f32 v[98:99], v[104:105], v[102:103]
	v_pk_add_f32 v[100:101], v[108:109], v[106:107]
	s_and_b64 s[0:1], exec, s[0:1]
	v_pk_add_f32 v[98:99], v[100:101], v[98:99]
	s_or_b64 s[8:9], s[0:1], s[8:9]
	v_pk_add_f32 v[96:97], v[98:99], v[96:97]
	v_lshl_add_u64 v[134:135], v[134:135], 0, s[6:7]
	v_add_f32_e32 v96, v96, v97
	v_mov_b32_e32 v152, v155
	s_nop 0
	v_add_f32_dpp v96, v96, v96 row_ror:1 row_mask:0xf bank_mask:0xf bound_ctrl:1
	s_nop 1
	v_add_f32_dpp v96, v96, v96 row_ror:2 row_mask:0xf bank_mask:0xf bound_ctrl:1
	s_nop 1
	v_add_f32_dpp v96, v96, v96 row_ror:4 row_mask:0xf bank_mask:0xf bound_ctrl:1
	s_nop 1
	v_add_f32_dpp v96, v96, v96 row_ror:8 row_mask:0xf bank_mask:0xf bound_ctrl:1
	s_nop 0
	v_readlane_b32 s17, v96, 16
	v_readlane_b32 s18, v96, 48
	v_readlane_b32 s2, v96, 0
	v_readlane_b32 s3, v96, 32
	v_mov_b32_e32 v96, s17
	v_mov_b32_e32 v97, s18
	v_pk_add_f32 v[96:97], s[2:3], v[96:97]
	s_nop 0
	v_add_f32_e32 v96, v96, v97
	v_mul_f32_e32 v96, 0x3a000000, v96
	v_pk_add_f32 v[136:137], v[136:137], v[96:97] op_sel_hi:[1,0] neg_lo:[0,1] neg_hi:[0,1]
	v_pk_add_f32 v[106:107], v[148:149], v[96:97] op_sel_hi:[1,0] neg_lo:[0,1] neg_hi:[0,1]
	v_pk_mul_f32 v[148:149], v[136:137], v[136:137]
	v_pk_add_f32 v[120:121], v[120:121], v[96:97] op_sel_hi:[1,0] neg_lo:[0,1] neg_hi:[0,1]
	v_pk_add_f32 v[108:109], v[150:151], v[96:97] op_sel_hi:[1,0] neg_lo:[0,1] neg_hi:[0,1]
	v_pk_mul_f32 v[150:151], v[120:121], v[120:121]
	v_add_f32_e32 v128, v149, v148
	v_pk_add_f32 v[110:111], v[124:125], v[96:97] op_sel_hi:[1,0] neg_lo:[0,1] neg_hi:[0,1]
	v_add_f32_e32 v128, v151, v128
	v_pk_mul_f32 v[124:125], v[110:111], v[110:111]
	v_add_f32_e32 v128, v150, v128
	v_pk_add_f32 v[126:127], v[126:127], v[96:97] op_sel_hi:[1,0] neg_lo:[0,1] neg_hi:[0,1]
	v_add_f32_e32 v125, v125, v128
	v_pk_add_f32 v[104:105], v[146:147], v[96:97] op_sel_hi:[1,0] neg_lo:[0,1] neg_hi:[0,1]
	v_pk_mul_f32 v[146:147], v[126:127], v[126:127]
	v_add_f32_e32 v124, v124, v125
	v_pk_add_f32 v[122:123], v[122:123], v[96:97] op_sel_hi:[1,0] neg_lo:[0,1] neg_hi:[0,1]
	v_add_f32_e32 v124, v147, v124
	v_pk_mul_f32 v[160:161], v[122:123], v[122:123]
	v_add_f32_e32 v124, v146, v124
	v_pk_add_f32 v[138:139], v[138:139], v[96:97] op_sel_hi:[1,0] neg_lo:[0,1] neg_hi:[0,1]
	v_add_f32_e32 v124, v161, v124
	v_pk_mul_f32 v[162:163], v[138:139], v[138:139]
	v_add_f32_e32 v124, v160, v124
	v_pk_add_f32 v[142:143], v[142:143], v[96:97] op_sel_hi:[1,0] neg_lo:[0,1] neg_hi:[0,1]
	v_add_f32_e32 v124, v163, v124
	v_pk_mul_f32 v[156:157], v[142:143], v[142:143]
	v_add_f32_e32 v124, v162, v124
	v_pk_add_f32 v[114:115], v[114:115], v[96:97] op_sel_hi:[1,0] neg_lo:[0,1] neg_hi:[0,1]
	v_add_f32_e32 v124, v157, v124
	v_pk_mul_f32 v[158:159], v[114:115], v[114:115]
	v_add_f32_e32 v124, v156, v124
	v_pk_add_f32 v[112:113], v[112:113], v[96:97] op_sel_hi:[1,0] neg_lo:[0,1] neg_hi:[0,1]
	v_add_f32_e32 v124, v159, v124
	v_pk_mul_f32 v[168:169], v[112:113], v[112:113]
	v_add_f32_e32 v124, v158, v124
	v_pk_add_f32 v[116:117], v[116:117], v[96:97] op_sel_hi:[1,0] neg_lo:[0,1] neg_hi:[0,1]
	v_add_f32_e32 v124, v169, v124
	v_pk_mul_f32 v[170:171], v[116:117], v[116:117]
	v_add_f32_e32 v124, v168, v124
	v_pk_add_f32 v[118:119], v[118:119], v[96:97] op_sel_hi:[1,0] neg_lo:[0,1] neg_hi:[0,1]
	v_add_f32_e32 v124, v171, v124
	v_pk_mul_f32 v[164:165], v[118:119], v[118:119]
	v_add_f32_e32 v124, v170, v124
	v_pk_add_f32 v[140:141], v[140:141], v[96:97] op_sel_hi:[1,0] neg_lo:[0,1] neg_hi:[0,1]
	v_add_f32_e32 v124, v165, v124
	v_pk_mul_f32 v[166:167], v[140:141], v[140:141]
	v_add_f32_e32 v124, v164, v124
	v_pk_add_f32 v[144:145], v[144:145], v[96:97] op_sel_hi:[1,0] neg_lo:[0,1] neg_hi:[0,1]
	v_add_f32_e32 v124, v167, v124
	v_pk_mul_f32 v[96:97], v[144:145], v[144:145]
	v_add_f32_e32 v124, v166, v124
	v_add_f32_e32 v97, v97, v124
	v_pk_mul_f32 v[98:99], v[104:105], v[104:105]
	v_add_f32_e32 v96, v96, v97
	v_add_f32_e32 v96, v99, v96
	v_pk_mul_f32 v[100:101], v[106:107], v[106:107]
	v_add_f32_e32 v96, v98, v96
	v_add_f32_e32 v96, v101, v96
	v_pk_mul_f32 v[102:103], v[108:109], v[108:109]
	v_add_f32_e32 v96, v100, v96
	v_add_f32_e32 v96, v103, v96
	v_add_f32_e32 v96, v102, v96
	s_nop 1
	v_add_f32_dpp v96, v96, v96 row_ror:1 row_mask:0xf bank_mask:0xf bound_ctrl:1
	s_nop 1
	v_add_f32_dpp v96, v96, v96 row_ror:2 row_mask:0xf bank_mask:0xf bound_ctrl:1
	s_nop 1
	v_add_f32_dpp v96, v96, v96 row_ror:4 row_mask:0xf bank_mask:0xf bound_ctrl:1
	s_nop 1
	v_add_f32_dpp v96, v96, v96 row_ror:8 row_mask:0xf bank_mask:0xf bound_ctrl:1
	s_nop 0
	v_readlane_b32 s17, v96, 16
	v_readlane_b32 s18, v96, 48
	v_readlane_b32 s2, v96, 0
	v_readlane_b32 s3, v96, 32
	v_mov_b32_e32 v96, s17
	v_mov_b32_e32 v97, s18
	v_pk_add_f32 v[96:97], s[2:3], v[96:97]
	s_nop 0
	v_add_f32_e32 v96, v96, v97
	v_fmamk_f32 v96, v96, 0x3a000000, v153
	v_mul_f32_e32 v97, 0x4f800000, v96
	v_cmp_gt_f32_e32 vcc, s16, v96
	s_nop 1
	v_cndmask_b32_e32 v96, v96, v97, vcc
	v_sqrt_f32_e32 v97, v96
	s_nop 0
	v_add_u32_e32 v98, -1, v97
	v_fma_f32 v99, -v98, v97, v96
	v_cmp_ge_f32_e64 s[2:3], 0, v99
	v_add_u32_e32 v99, 1, v97
	s_nop 0
	v_cndmask_b32_e64 v98, v97, v98, s[2:3]
	v_fma_f32 v97, -v99, v97, v96
	v_cmp_lt_f32_e64 s[2:3], 0, v97
	s_nop 1
	v_cndmask_b32_e64 v97, v98, v99, s[2:3]
	v_mul_f32_e32 v98, 0x37800000, v97
	v_cndmask_b32_e32 v97, v97, v98, vcc
	v_cmp_class_f32_e32 vcc, v96, v154
	s_nop 1
	v_cndmask_b32_e32 v96, v97, v96, vcc
	v_div_scale_f32 v97, s[2:3], v96, v96, 1.0
	v_rcp_f32_e32 v98, v97
	s_nop 0
	v_fma_f32 v99, -v97, v98, 1.0
	v_fmac_f32_e32 v98, v99, v98
	v_div_scale_f32 v99, vcc, 1.0, v96, 1.0
	v_mul_f32_e32 v100, v99, v98
	v_fma_f32 v101, -v97, v100, v99
	v_fmac_f32_e32 v100, v101, v98
	v_fma_f32 v97, -v97, v100, v99
	v_div_fmas_f32 v97, v97, v98, v100
	v_div_fixup_f32 v124, v97, v96, 1.0
	v_pk_mul_f32 v[96:97], v[136:137], v[124:125] op_sel_hi:[1,0]
	v_pk_mul_f32 v[98:99], v[120:121], v[124:125] op_sel_hi:[1,0]
	v_pk_mul_f32 v[100:101], v[110:111], v[124:125] op_sel_hi:[1,0]
	v_pk_mul_f32 v[102:103], v[126:127], v[124:125] op_sel_hi:[1,0]
	s_waitcnt vmcnt(2)
	v_pk_fma_f32 v[96:97], v[52:53], v[96:97], v[40:41] op_sel:[0,1,0] op_sel_hi:[1,0,1]
	v_pk_fma_f32 v[98:99], v[54:55], v[98:99], v[42:43] op_sel:[0,1,0] op_sel_hi:[1,0,1]
	s_waitcnt vmcnt(0)
	v_pk_fma_f32 v[100:101], v[60:61], v[100:101], v[48:49] op_sel:[0,1,0] op_sel_hi:[1,0,1]
	v_pk_fma_f32 v[102:103], v[62:63], v[102:103], v[50:51] op_sel:[0,1,0] op_sel_hi:[1,0,1]
	global_store_dwordx4 v[132:133], v[96:99], off offset:-4096 nt
	global_store_dwordx4 v[132:133], v[100:103], off offset:-4080 nt
	s_nop 0
	v_pk_mul_f32 v[96:97], v[122:123], v[124:125] op_sel_hi:[1,0]
	v_pk_mul_f32 v[98:99], v[138:139], v[124:125] op_sel_hi:[1,0]
	v_pk_mul_f32 v[100:101], v[142:143], v[124:125] op_sel_hi:[1,0]
	v_pk_mul_f32 v[102:103], v[114:115], v[124:125] op_sel_hi:[1,0]
	v_pk_fma_f32 v[96:97], v[56:57], v[96:97], v[44:45] op_sel:[0,1,0] op_sel_hi:[1,0,1]
	v_pk_fma_f32 v[98:99], v[58:59], v[98:99], v[46:47] op_sel:[0,1,0] op_sel_hi:[1,0,1]
	v_pk_fma_f32 v[100:101], v[36:37], v[100:101], v[28:29] op_sel:[0,1,0] op_sel_hi:[1,0,1]
	v_pk_fma_f32 v[102:103], v[38:39], v[102:103], v[30:31] op_sel:[0,1,0] op_sel_hi:[1,0,1]
	global_store_dwordx4 v[132:133], v[96:99], off offset:-2048 nt
	global_store_dwordx4 v[132:133], v[100:103], off offset:-2032 nt
	v_mov_b64_e32 v[122:123], v[78:79]
	v_pk_mul_f32 v[96:97], v[112:113], v[124:125] op_sel_hi:[1,0]
	v_pk_mul_f32 v[98:99], v[116:117], v[124:125] op_sel_hi:[1,0]
	v_pk_mul_f32 v[100:101], v[118:119], v[124:125] op_sel_hi:[1,0]
	v_pk_mul_f32 v[102:103], v[140:141], v[124:125] op_sel_hi:[1,0]
	v_pk_fma_f32 v[96:97], v[16:17], v[96:97], v[4:5] op_sel:[0,1,0] op_sel_hi:[1,0,1]
	v_pk_fma_f32 v[98:99], v[18:19], v[98:99], v[6:7] op_sel:[0,1,0] op_sel_hi:[1,0,1]
	v_pk_fma_f32 v[100:101], v[20:21], v[100:101], v[8:9] op_sel:[0,1,0] op_sel_hi:[1,0,1]
	v_pk_fma_f32 v[102:103], v[22:23], v[102:103], v[10:11] op_sel:[0,1,0] op_sel_hi:[1,0,1]
	global_store_dwordx4 v[132:133], v[96:99], off nt
	global_store_dwordx4 v[132:133], v[100:103], off offset:16 nt
	v_mov_b64_e32 v[114:115], v[74:75]
	v_pk_mul_f32 v[96:97], v[144:145], v[124:125] op_sel_hi:[1,0]
	v_pk_mul_f32 v[98:99], v[104:105], v[124:125] op_sel_hi:[1,0]
	v_pk_mul_f32 v[100:101], v[106:107], v[124:125] op_sel_hi:[1,0]
	v_pk_mul_f32 v[102:103], v[108:109], v[124:125] op_sel_hi:[1,0]
	v_pk_fma_f32 v[96:97], v[12:13], v[96:97], v[0:1] op_sel:[0,1,0] op_sel_hi:[1,0,1]
	v_pk_fma_f32 v[98:99], v[14:15], v[98:99], v[2:3] op_sel:[0,1,0] op_sel_hi:[1,0,1]
	v_pk_fma_f32 v[100:101], v[32:33], v[100:101], v[24:25] op_sel:[0,1,0] op_sel_hi:[1,0,1]
	v_pk_fma_f32 v[102:103], v[34:35], v[102:103], v[26:27] op_sel:[0,1,0] op_sel_hi:[1,0,1]
	global_store_dwordx4 v[132:133], v[96:99], off offset:2048 nt
	global_store_dwordx4 v[132:133], v[100:103], off offset:2064 nt
	v_mov_b64_e32 v[106:107], v[70:71]
	v_mov_b64_e32 v[98:99], v[66:67]
	v_mov_b64_e32 v[102:103], v[82:83]
	v_mov_b64_e32 v[110:111], v[86:87]
	v_mov_b64_e32 v[118:119], v[90:91]
	v_mov_b64_e32 v[126:127], v[94:95]
	v_lshl_add_u64 v[132:133], v[132:133], 0, s[4:5]
	v_mov_b64_e32 v[96:97], v[64:65]
	v_mov_b64_e32 v[104:105], v[68:69]
	v_mov_b64_e32 v[112:113], v[72:73]
	v_mov_b64_e32 v[120:121], v[76:77]
	v_mov_b64_e32 v[100:101], v[80:81]
	v_mov_b64_e32 v[108:109], v[84:85]
	v_mov_b64_e32 v[116:117], v[88:89]
	v_mov_b64_e32 v[124:125], v[92:93]
	s_andn2_b64 exec, exec, s[8:9]
	s_cbranch_execz .LBB0_2393
